# plain-copy units of the attention phase moved into the gate/up GEMM epilogues: each wave loads two 12KB row groups at epilogue start into dead fragment/accumulator VGPRs via buffer_load, stores them a
# speedup vs baseline: 1.0429x; 1.0383x over previous
.LBB0_1209:
	v_readlane_b32 s10, v240, 0
	s_add_i32 s12, s8, s10
	s_lshl_b32 s8, s95, 8
	s_add_i32 s8, s8, s15
	s_ashr_i32 s9, s8, 7
	v_readlane_b32 s11, v240, 1
	s_mul_hi_i32 s10, s9, 0x55555556
	s_lshr_b32 s11, s10, 31
	s_add_i32 s10, s10, s11
	s_mul_i32 s11, s14, 3
	s_add_i32 s11, s10, s11
	s_mul_i32 s10, s10, 3
	s_mul_i32 s11, s11, 3
	s_sub_i32 s10, s9, s10
	s_add_i32 s11, s11, s10
	s_mul_hi_i32 s10, s8, 0x30c30c31
	s_lshr_b32 s16, s10, 31
	s_ashr_i32 s10, s10, 4
	s_add_i32 s10, s10, s16
	s_lshl_b32 s16, s10, 3
	s_or_b32 s16, s16, s14
	s_mulk_i32 s10, 0x54
	s_mulk_i32 s16, 0x54
	s_sub_i32 s10, s8, s10
	s_add_i32 s13, s12, 0x2a00
	s_add_i32 s96, s12, 0xffffea00
	s_add_i32 s16, s16, s10
	s_cmp_lt_u32 s9, 12
	s_cselect_b32 s10, s19, s2
	s_add_i32 s10, s10, s9
	s_cmp_lt_i32 s9, 9
	s_cselect_b32 s9, s11, s10
	s_lshl_b32 s9, s9, 7
	s_add_i32 s17, s9, s35
	s_cmpk_lt_i32 s8, 0x540
	s_cselect_b32 s10, s16, -1
	s_and_b64 s[8:9], s[58:59], exec
	s_cselect_b32 s16, s12, s10
	s_cmpk_gt_i32 s12, 0x29ff
	s_cselect_b64 s[8:9], -1, 0
	s_and_b64 s[10:11], s[8:9], exec
	s_cselect_b32 s97, -1, s16
	s_or_b64 s[8:9], s[8:9], s[58:59]
	s_cmpk_lt_u32 s96, 0x1800
	s_cselect_b64 s[10:11], -1, 0
	s_and_b64 s[74:75], s[8:9], s[10:11]
	s_and_b64 s[8:9], s[58:59], exec
	s_cselect_b32 s8, s13, s17
	s_cmpk_lt_i32 s12, 0x3800
	s_mov_b32 s40, s82
	s_cselect_b32 s52, s8, -1
	s_mov_b64 s[76:77], -1
	s_mov_b32 s10, s57
	s_branch .LBB0_1212

.LBB0_1649:
	s_or_b64 exec, exec, s[6:7]
	s_add_u32 s8, s30, 0xfc00000
	s_addc_u32 s9, s31, 0
	v_mov_b32_e32 v10, v164
	s_waitcnt lgkmcnt(0)
	s_barrier
	s_cmpk_gt_i32 s69, 0x5d7
	v_readfirstlane_b32 s7, v10
	s_cbranch_scc1 .LBB0_1665
	v_writelane_b32 v247, s78, 0
	v_writelane_b32 v247, s79, 1
	v_writelane_b32 v247, s4, 2
	v_writelane_b32 v247, s5, 3
	s_lshr_b32 s32, s69, 7
	s_lshl_b32 s32, s32, 3
	s_load_dwordx2 s[96:97], s[0:1], s32 offset:0x20
	s_load_dwordx2 s[76:77], s[0:1], 0xa0
	s_and_b32 s100, s69, 0x7f
	s_mul_i32 s100, s100, 0x300000
	s_mov_b32 s101, 0x1ee80000
	s_cmp_lt_u32 s69, 0x80
	s_cselect_b32 s101, 0x6e80000, s101
	v_and_b32_e32 v246, 63, v164
	v_lshlrev_b32_e32 v246, 4, v246
	s_waitcnt lgkmcnt(0)
	s_add_u32 s96, s96, s100
	s_addc_u32 s97, s97, 0
	s_add_u32 s96, s96, 0x3000
	s_addc_u32 s97, s97, 0
	s_and_b32 s97, s97, 0xffff
	s_mov_b32 s98, 0x300000
	s_mov_b32 s99, 0x20000
	s_add_u32 s76, s76, s101
	s_addc_u32 s77, s77, 0
	s_add_u32 s76, s76, s100
	s_addc_u32 s77, s77, 0
	s_and_b32 s77, s77, 0xffff
	s_mov_b32 s78, 0x300000
	s_mov_b32 s79, 0x20000
	s_lshr_b32 s32, s7, 6
	s_mul_i32 s101, s32, 0x0
	s_add_u32 s100, s101, 0x0
	s_mul_i32 s5, s32, 0x6000
	s_add_u32 s5, s5, 0x0
	s_mov_b32 s32, 0
	s_mov_b32 s4, 0
	v_add_u32_e32 v238, 0x1000, v246
	v_add_u32_e32 v239, 0x2000, v246
	s_mov_b32 s100, 0x70000000
	s_mov_b32 s101, 0x70000000
	v_lshlrev_b32_e32 v0, 4, v10
	v_add_u32_e32 v1, 0x2000, v0
	v_ashrrev_i32_e32 v2, 31, v1
	v_lshrrev_b32_e32 v2, 22, v2
	v_add_u32_e32 v2, v1, v2
	v_ashrrev_i32_e32 v8, 10, v2
	v_mul_i32_i24_e32 v2, 0x400, v8
	v_sub_u32_e32 v1, v1, v2
	v_lshrrev_b32_e32 v2, 4, v1
	v_bitop3_b32 v1, v2, v1, 32 bitop3:0x6c
	v_ashrrev_i32_e32 v2, 31, v1
	v_lshrrev_b32_e32 v2, 26, v2
	v_add_u32_e32 v2, v1, v2
	v_lshlrev_b32_e32 v3, 3, v8
	v_ashrrev_i32_e32 v9, 6, v2
	v_and_b32_e32 v3, -16, v3
	v_add_u32_e32 v3, v9, v3
	v_and_b32_e32 v4, 3, v9
	s_mov_b32 s6, 0x1fffe0
	v_lshrrev_b32_e32 v5, 2, v3
	v_lshlrev_b32_e32 v6, 1, v3
	v_and_b32_e32 v2, 0xc0, v2
	v_and_or_b32 v4, v3, s6, v4
	v_and_b32_e32 v5, 4, v5
	v_and_b32_e32 v6, 24, v6
	v_sub_u32_e32 v1, v1, v2
	v_mov_b32_e32 v2, 1
	v_or3_b32 v4, v4, v5, v6
	v_lshlrev_b32_e32 v5, 5, v8
	v_ashrrev_i16_sdwa v1, v2, sext(v1) dst_sel:DWORD dst_unused:UNUSED_PAD src0_sel:DWORD src1_sel:BYTE_0
	v_and_b32_e32 v5, 32, v5
	v_bfe_i32 v11, v1, 0, 16
	v_add_lshl_u32 v1, v5, v11, 1
	v_lshl_add_u32 v130, v4, 11, v1
	v_lshl_add_u32 v132, v3, 11, v1
	v_bfe_i32 v1, v10, 27, 1
	v_lshrrev_b32_e32 v1, 22, v1
	v_add_u32_e32 v1, v0, v1
	v_and_b32_e32 v1, 0xfffffc00, v1
	v_sub_u32_e32 v0, v0, v1
	v_lshrrev_b32_e32 v1, 4, v0
	v_ashrrev_i32_e32 v3, 31, v10
	v_bitop3_b32 v0, v1, v0, 32 bitop3:0x6c
	v_lshrrev_b32_e32 v3, 26, v3
	v_ashrrev_i32_e32 v1, 31, v0
	v_add_u32_e32 v3, v10, v3
	v_lshrrev_b32_e32 v1, 26, v1
	v_ashrrev_i32_e32 v13, 6, v3
	v_add_u32_e32 v1, v0, v1
	v_lshlrev_b32_e32 v3, 3, v13
	v_ashrrev_i32_e32 v12, 6, v1
	v_and_b32_e32 v3, -16, v3
	v_add_u32_e32 v3, v12, v3
	v_and_b32_e32 v4, 3, v12
	s_ashr_i32 s14, s69, 31
	v_and_or_b32 v4, v3, s6, v4
	s_lshr_b32 s6, s14, 29
	s_add_i32 s6, s69, s6
	s_ashr_i32 s2, s7, 6
	s_ashr_i32 s11, s6, 3
	s_and_b32 s6, s6, -8
	s_ashr_i32 s10, s7, 8
	s_lshl_b32 s3, s2, 10
	s_sub_i32 s6, s69, s6
	s_cmp_lt_i32 s6, 0
	s_movk_i32 s15, 0xbc
	s_cselect_b32 s18, s15, 0xbb
	s_mul_i32 s6, s6, s18
	s_add_i32 s6, s6, s11
	s_mul_hi_i32 s11, s6, 0x2e8ba2e9
	s_lshr_b32 s18, s11, 31
	s_ashr_i32 s11, s11, 5
	v_lshrrev_b32_e32 v5, 2, v3
	v_lshlrev_b32_e32 v6, 1, v3
	v_and_b32_e32 v1, 0xc0, v1
	s_add_i32 s11, s11, s18
	v_and_b32_e32 v5, 4, v5
	v_and_b32_e32 v6, 24, v6
	v_sub_u32_e32 v0, v0, v1
	s_lshl_b32 s22, s11, 3
	v_or3_b32 v4, v4, v5, v6
	v_lshlrev_b32_e32 v5, 5, v13
	v_ashrrev_i16_sdwa v0, v2, sext(v0) dst_sel:DWORD dst_unused:UNUSED_PAD src0_sel:DWORD src1_sel:BYTE_0
	s_sub_i32 s18, 0x44, s22
	s_mulk_i32 s11, 0xb0
	v_and_b32_e32 v5, 32, v5
	v_bfe_i32 v14, v0, 0, 16
	s_min_u32 s23, s18, 8
	s_sub_i32 s11, s6, s11
	v_add_lshl_u32 v0, v5, v14, 1
	s_sext_i32_i16 s6, s11
	v_cvt_f32_ubyte0_e32 v2, s23
	v_lshl_add_u32 v134, v4, 11, v0
	v_cvt_f32_i32_e32 v1, s6
	v_rcp_iflag_f32_e32 v4, v2
	v_lshl_add_u32 v136, v3, 11, v0
	s_ashr_i32 s6, s6, 30
	s_or_b32 s6, s6, 1
	v_mul_f32_e32 v0, v1, v4
	v_trunc_f32_e32 v0, v0
	v_fma_f32 v1, -v0, v2, v1
	v_cvt_i32_f32_e32 v0, v0
	v_cmp_ge_f32_e64 s[18:19], |v1|, v2
	s_and_b64 s[18:19], s[18:19], exec
	s_cselect_b32 s6, s6, 0
	v_readfirstlane_b32 s18, v0
	s_add_i32 s6, s18, s6
	s_mul_i32 s18, s6, s23
	s_sub_i32 s11, s11, s18
	s_sext_i32_i16 s11, s11
	s_add_i32 s56, s22, s11
	s_ashr_i32 s57, s56, 31
	s_bfe_i64 s[18:19], s[6:7], 0x100000
	s_lshl_b64 s[22:23], s[56:57], 19
	s_lshl_b64 s[18:19], s[18:19], 19
	s_add_u32 s60, s92, s18
	s_addc_u32 s61, s93, s19
	s_add_i32 s18, s3, 0
	s_add_i32 m0, s18, 0x10000
	v_mov_b32_e32 v139, 0
	global_load_lds_dwordx4 v134, s[60:61]
	s_add_i32 m0, s18, 0x12000
	s_add_u32 s24, s60, 0x40000
	global_load_lds_dwordx4 v130, s[60:61]
	s_addc_u32 s25, s61, 0
	s_add_i32 m0, s18, 0x14000
	v_mov_b32_e32 v135, v139
	global_load_lds_dwordx4 v134, s[24:25]
	s_add_i32 m0, s18, 0x16000
	s_add_u32 s58, s94, s22
	s_addc_u32 s59, s95, s23
	s_add_i32 s19, s18, 0x2000
	global_load_lds_dwordx4 v130, s[24:25]
	s_mov_b32 m0, s18
	s_add_u32 s22, s58, 0x40000
	global_load_lds_dwordx4 v136, s[58:59]
	s_mov_b32 m0, s19
	s_addc_u32 s23, s59, 0
	s_add_i32 s35, s18, 0x4000
	global_load_lds_dwordx4 v132, s[58:59]
	s_mov_b32 m0, s35
	s_add_i32 s43, s18, 0x6000
	global_load_lds_dwordx4 v136, s[22:23]
	s_mov_b32 m0, s43
	v_mov_b32_e32 v131, v139
	global_load_lds_dwordx4 v132, s[22:23]
	v_mov_b32_e32 v137, v139
	v_mov_b32_e32 v133, v139
	s_cmp_eq_u32 s10, 1
	s_mov_b32 s11, 0
	v_lshl_add_u64 v[6:7], s[60:61], 0, v[134:135]
	v_lshl_add_u64 v[4:5], s[60:61], 0, v[130:131]
	v_lshl_add_u64 v[0:1], s[58:59], 0, v[136:137]
	s_cselect_b64 s[22:23], -1, 0
	s_cmp_lg_u32 s10, 1
	v_lshl_add_u64 v[2:3], s[58:59], 0, v[132:133]
	s_cbranch_scc1 .LBB0_1652
	s_barrier

.LBB0_1661:
	s_add_u32 vcc_lo, s5, 0xf0000
	buffer_load_dwordx4 v[166:169], v246, s[96:99], s5 offen nt
	buffer_load_dwordx4 v[170:173], v246, s[96:99], s5 offen offset:1024 nt
	buffer_load_dwordx4 v[174:177], v246, s[96:99], s5 offen offset:2048 nt
	buffer_load_dwordx4 v[178:181], v246, s[96:99], s5 offen offset:3072 nt
	buffer_load_dwordx4 v[182:185], v238, s[96:99], s5 offen nt
	buffer_load_dwordx4 v[186:189], v238, s[96:99], s5 offen offset:1024 nt
	buffer_load_dwordx4 v[190:193], v238, s[96:99], s5 offen offset:2048 nt
	buffer_load_dwordx4 v[194:197], v238, s[96:99], s5 offen offset:3072 nt
	buffer_load_dwordx4 v[198:201], v239, s[96:99], s5 offen nt
	buffer_load_dwordx4 v[202:205], v239, s[96:99], s5 offen offset:1024 nt
	buffer_load_dwordx4 v[206:209], v239, s[96:99], s5 offen offset:2048 nt
	buffer_load_dwordx4 v[210:213], v239, s[96:99], s5 offen offset:3072 nt
	buffer_load_dwordx4 v[158:161], v246, s[96:99], vcc_lo offen nt
	buffer_load_dwordx4 v[214:217], v246, s[96:99], vcc_lo offen offset:1024 nt
	buffer_load_dwordx4 v[218:221], v246, s[96:99], vcc_lo offen offset:2048 nt
	buffer_load_dwordx4 v[222:225], v246, s[96:99], vcc_lo offen offset:3072 nt
	buffer_load_dwordx4 v[226:229], v238, s[96:99], vcc_lo offen nt
	buffer_load_dwordx4 v[230:233], v238, s[96:99], vcc_lo offen offset:1024 nt
	buffer_load_dwordx4 v[234:237], v238, s[96:99], vcc_lo offen offset:2048 nt
	buffer_load_dwordx4 v[242:245], v238, s[96:99], vcc_lo offen offset:3072 nt
	v_mul_f32_e32 v153, 0xbfb8aa3b, v124
	v_exp_f32_e32 v153, v153
	v_mul_f32_e32 v154, 0xbfb8aa3b, v125
	v_exp_f32_e32 v155, v154
	s_lshl_b32 s48, s2, 7
	v_add_f32_e32 v153, 1.0, v153
	v_rcp_f32_e32 v154, v153
	v_add_f32_e32 v153, 1.0, v155
	v_mul_f32_e32 v155, 0xbfb8aa3b, v126
	v_exp_f32_e32 v156, v155
	v_mul_f32_e32 v155, 0xbfb8aa3b, v127
	v_exp_f32_e32 v157, v155
	v_rcp_f32_e32 v155, v153
	v_add_f32_e32 v153, 1.0, v156
	v_rcp_f32_e32 v156, v153
	v_add_f32_e32 v153, 1.0, v157
	v_rcp_f32_e32 v157, v153
	v_pk_mul_f32 v[124:125], v[124:125], v[154:155]
	v_mul_f32_e32 v153, 0xbfb8aa3b, v118
	v_pk_mul_f32 v[120:121], v[120:121], v[124:125]
	v_pk_mul_f32 v[124:125], v[126:127], v[156:157]
	v_mul_f32_e32 v126, 0xbfb8aa3b, v116
	v_mul_f32_e32 v127, 0xbfb8aa3b, v117
	v_exp_f32_e32 v126, v126
	v_exp_f32_e32 v127, v127
	v_exp_f32_e32 v153, v153
	v_mul_f32_e32 v154, 0xbfb8aa3b, v119
	v_exp_f32_e32 v155, v154
	v_add_f32_e32 v126, 1.0, v126
	v_add_f32_e32 v127, 1.0, v127
	v_add_f32_e32 v153, 1.0, v153
	v_rcp_f32_e32 v126, v126
	v_rcp_f32_e32 v127, v127
	v_rcp_f32_e32 v154, v153
	v_add_f32_e32 v153, 1.0, v155
	v_rcp_f32_e32 v155, v153
	v_pk_mul_f32 v[116:117], v[116:117], v[126:127]
	v_lshl_add_u32 v152, s56, 8, v129
	v_pk_mul_f32 v[112:113], v[112:113], v[116:117]
	v_pk_mul_f32 v[116:117], v[118:119], v[154:155]
	s_ashr_i32 s49, s48, 31
	v_pk_mul_f32 v[114:115], v[114:115], v[116:117]
	v_pk_mul_f32 v[122:123], v[122:123], v[124:125]
	v_cvt_pk_bf16_f32 v124, v120, v121
	v_mov_b64_e32 v[120:121], s[8:9]
	v_cvt_pk_bf16_f32 v112, v112, v113
	v_cvt_pk_bf16_f32 v113, v114, v115
	v_mul_f32_e32 v114, 0xbfb8aa3b, v108
	v_mul_f32_e32 v115, 0xbfb8aa3b, v109
	v_cvt_pk_bf16_f32 v125, v122, v123
	v_mad_i64_i32 v[122:123], s[50:51], v152, s66, v[120:121]
	s_lshl_b64 s[56:57], s[48:49], 1
	v_exp_f32_e32 v114, v114
	v_exp_f32_e32 v115, v115
	v_lshl_add_u64 v[122:123], v[122:123], 0, s[56:57]
	v_lshl_add_u64 v[122:123], v[122:123], 0, s[10:11]
	v_lshl_add_u64 v[122:123], v[122:123], 0, v[138:139]
	global_store_dwordx2 v[122:123], v[112:113], off offset:128
	v_add_f32_e32 v112, 1.0, v114
	v_add_f32_e32 v113, 1.0, v115
	v_mul_f32_e32 v114, 0xbfb8aa3b, v110
	v_mul_f32_e32 v115, 0xbfb8aa3b, v111
	v_exp_f32_e32 v114, v114
	v_exp_f32_e32 v115, v115
	v_rcp_f32_e32 v112, v112
	v_rcp_f32_e32 v113, v113
	v_add_f32_e32 v114, 1.0, v114
	v_add_f32_e32 v115, 1.0, v115
	v_rcp_f32_e32 v114, v114
	v_rcp_f32_e32 v115, v115
	v_pk_mul_f32 v[108:109], v[108:109], v[112:113]
	v_or_b32_e32 v116, 16, v152
	v_pk_mul_f32 v[104:105], v[104:105], v[108:109]
	v_pk_mul_f32 v[108:109], v[110:111], v[114:115]
	buffer_load_dwordx4 v[112:115], v239, s[96:99], vcc_lo offen nt
	v_mul_f32_e32 v110, 0xbfb8aa3b, v102
	v_pk_mul_f32 v[106:107], v[106:107], v[108:109]
	v_mul_f32_e32 v108, 0xbfb8aa3b, v100
	v_mul_f32_e32 v109, 0xbfb8aa3b, v101
	v_exp_f32_e32 v108, v108
	v_exp_f32_e32 v109, v109
	v_mul_f32_e32 v111, 0xbfb8aa3b, v103
	v_exp_f32_e32 v110, v110
	v_exp_f32_e32 v111, v111
	v_add_f32_e32 v108, 1.0, v108
	v_add_f32_e32 v109, 1.0, v109
	v_rcp_f32_e32 v108, v108
	v_rcp_f32_e32 v109, v109
	v_add_f32_e32 v110, 1.0, v110
	v_add_f32_e32 v111, 1.0, v111
	v_rcp_f32_e32 v110, v110
	v_rcp_f32_e32 v111, v111
	v_pk_mul_f32 v[100:101], v[100:101], v[108:109]
	v_cvt_pk_bf16_f32 v104, v104, v105
	v_pk_mul_f32 v[96:97], v[96:97], v[100:101]
	v_pk_mul_f32 v[100:101], v[102:103], v[110:111]
	buffer_load_dwordx4 v[108:111], v239, s[96:99], vcc_lo offen offset:1024 nt
	v_cvt_pk_bf16_f32 v96, v96, v97
	v_pk_mul_f32 v[98:99], v[98:99], v[100:101]
	v_cvt_pk_bf16_f32 v105, v106, v107
	v_cvt_pk_bf16_f32 v97, v98, v99
	v_mul_f32_e32 v98, 0xbfb8aa3b, v92
	v_mul_f32_e32 v99, 0xbfb8aa3b, v93
	v_mad_i64_i32 v[106:107], s[48:49], v116, s66, v[120:121]
	buffer_load_dwordx4 v[116:119], v239, s[96:99], vcc_lo offen offset:2048 nt
	v_exp_f32_e32 v98, v98
	v_exp_f32_e32 v99, v99
	v_lshl_add_u64 v[106:107], v[106:107], 0, s[56:57]
	v_lshl_add_u64 v[106:107], v[106:107], 0, s[10:11]
	v_lshl_add_u64 v[106:107], v[106:107], 0, v[138:139]
	global_store_dwordx2 v[106:107], v[96:97], off offset:128
	v_add_f32_e32 v96, 1.0, v98
	v_add_f32_e32 v97, 1.0, v99
	v_mul_f32_e32 v98, 0xbfb8aa3b, v94
	v_mul_f32_e32 v99, 0xbfb8aa3b, v95
	v_exp_f32_e32 v98, v98
	v_exp_f32_e32 v99, v99
	v_rcp_f32_e32 v96, v96
	v_rcp_f32_e32 v97, v97
	v_add_f32_e32 v98, 1.0, v98
	v_add_f32_e32 v99, 1.0, v99
	v_rcp_f32_e32 v98, v98
	v_rcp_f32_e32 v99, v99
	v_pk_mul_f32 v[92:93], v[92:93], v[96:97]
	v_or_b32_e32 v100, 32, v152
	v_pk_mul_f32 v[88:89], v[88:89], v[92:93]
	v_pk_mul_f32 v[92:93], v[94:95], v[98:99]
	buffer_load_dwordx4 v[96:99], v239, s[96:99], vcc_lo offen offset:3072 nt
	v_mul_f32_e32 v94, 0xbfb8aa3b, v86
	v_pk_mul_f32 v[90:91], v[90:91], v[92:93]
	v_mul_f32_e32 v92, 0xbfb8aa3b, v84
	v_mul_f32_e32 v93, 0xbfb8aa3b, v85
	v_exp_f32_e32 v92, v92
	v_exp_f32_e32 v93, v93
	v_mul_f32_e32 v95, 0xbfb8aa3b, v87
	v_exp_f32_e32 v94, v94
	v_exp_f32_e32 v95, v95
	v_add_f32_e32 v92, 1.0, v92
	v_add_f32_e32 v93, 1.0, v93
	v_rcp_f32_e32 v92, v92
	v_rcp_f32_e32 v93, v93
	v_add_f32_e32 v94, 1.0, v94
	v_add_f32_e32 v95, 1.0, v95
	v_rcp_f32_e32 v94, v94
	v_rcp_f32_e32 v95, v95
	v_pk_mul_f32 v[84:85], v[84:85], v[92:93]
	v_cvt_pk_bf16_f32 v88, v88, v89
	v_pk_mul_f32 v[80:81], v[80:81], v[84:85]
	v_pk_mul_f32 v[84:85], v[86:87], v[94:95]
	v_cvt_pk_bf16_f32 v80, v80, v81
	v_pk_mul_f32 v[82:83], v[82:83], v[84:85]
	v_cvt_pk_bf16_f32 v89, v90, v91
	v_cvt_pk_bf16_f32 v81, v82, v83
	v_mul_f32_e32 v82, 0xbfb8aa3b, v76
	v_mul_f32_e32 v83, 0xbfb8aa3b, v77
	v_mad_i64_i32 v[90:91], s[48:49], v100, s66, v[120:121]
	v_exp_f32_e32 v82, v82
	v_exp_f32_e32 v83, v83
	v_lshl_add_u64 v[90:91], v[90:91], 0, s[56:57]
	v_lshl_add_u64 v[90:91], v[90:91], 0, s[10:11]
	v_lshl_add_u64 v[90:91], v[90:91], 0, v[138:139]
	global_store_dwordx2 v[90:91], v[80:81], off offset:128
	v_add_f32_e32 v80, 1.0, v82
	v_add_f32_e32 v81, 1.0, v83
	v_mul_f32_e32 v82, 0xbfb8aa3b, v78
	v_mul_f32_e32 v83, 0xbfb8aa3b, v79
	v_exp_f32_e32 v82, v82
	v_exp_f32_e32 v83, v83
	v_rcp_f32_e32 v80, v80
	v_rcp_f32_e32 v81, v81
	v_add_f32_e32 v82, 1.0, v82
	v_add_f32_e32 v83, 1.0, v83
	v_rcp_f32_e32 v82, v82
	v_rcp_f32_e32 v83, v83
	v_pk_mul_f32 v[76:77], v[76:77], v[80:81]
	v_or_b32_e32 v84, 48, v152
	v_pk_mul_f32 v[72:73], v[72:73], v[76:77]
	v_pk_mul_f32 v[76:77], v[78:79], v[82:83]
	v_mul_f32_e32 v78, 0xbfb8aa3b, v70
	v_pk_mul_f32 v[74:75], v[74:75], v[76:77]
	v_mul_f32_e32 v76, 0xbfb8aa3b, v68
	v_mul_f32_e32 v77, 0xbfb8aa3b, v69
	v_exp_f32_e32 v76, v76
	v_exp_f32_e32 v77, v77
	v_mul_f32_e32 v79, 0xbfb8aa3b, v71
	v_exp_f32_e32 v78, v78
	v_exp_f32_e32 v79, v79
	v_add_f32_e32 v76, 1.0, v76
	v_add_f32_e32 v77, 1.0, v77
	v_rcp_f32_e32 v76, v76
	v_rcp_f32_e32 v77, v77
	v_add_f32_e32 v78, 1.0, v78
	v_add_f32_e32 v79, 1.0, v79
	v_rcp_f32_e32 v78, v78
	v_rcp_f32_e32 v79, v79
	v_pk_mul_f32 v[68:69], v[68:69], v[76:77]
	v_cvt_pk_bf16_f32 v72, v72, v73
	v_pk_mul_f32 v[64:65], v[64:65], v[68:69]
	v_pk_mul_f32 v[68:69], v[70:71], v[78:79]
	v_cvt_pk_bf16_f32 v64, v64, v65
	v_pk_mul_f32 v[66:67], v[66:67], v[68:69]
	v_cvt_pk_bf16_f32 v73, v74, v75
	v_cvt_pk_bf16_f32 v65, v66, v67
	v_mul_f32_e32 v66, 0xbfb8aa3b, v60
	v_mul_f32_e32 v67, 0xbfb8aa3b, v61
	v_mad_i64_i32 v[74:75], s[48:49], v84, s66, v[120:121]
	v_exp_f32_e32 v66, v66
	v_exp_f32_e32 v67, v67
	v_lshl_add_u64 v[74:75], v[74:75], 0, s[56:57]
	v_lshl_add_u64 v[74:75], v[74:75], 0, s[10:11]
	v_lshl_add_u64 v[74:75], v[74:75], 0, v[138:139]
	global_store_dwordx2 v[74:75], v[64:65], off offset:128
	v_add_f32_e32 v64, 1.0, v66
	v_add_f32_e32 v65, 1.0, v67
	v_mul_f32_e32 v66, 0xbfb8aa3b, v62
	v_mul_f32_e32 v67, 0xbfb8aa3b, v63
	v_exp_f32_e32 v66, v66
	v_exp_f32_e32 v67, v67
	v_rcp_f32_e32 v64, v64
	v_rcp_f32_e32 v65, v65
	v_add_f32_e32 v66, 1.0, v66
	v_add_f32_e32 v67, 1.0, v67
	v_rcp_f32_e32 v66, v66
	v_rcp_f32_e32 v67, v67
	v_pk_mul_f32 v[60:61], v[60:61], v[64:65]
	v_add_u32_e32 v68, 0x80, v152
	v_pk_mul_f32 v[56:57], v[56:57], v[60:61]
	v_pk_mul_f32 v[60:61], v[62:63], v[66:67]
	v_mul_f32_e32 v62, 0xbfb8aa3b, v54
	v_pk_mul_f32 v[58:59], v[58:59], v[60:61]
	v_mul_f32_e32 v60, 0xbfb8aa3b, v52
	v_mul_f32_e32 v61, 0xbfb8aa3b, v53
	v_exp_f32_e32 v60, v60
	v_exp_f32_e32 v61, v61
	v_mul_f32_e32 v63, 0xbfb8aa3b, v55
	v_exp_f32_e32 v62, v62
	v_exp_f32_e32 v63, v63
	v_add_f32_e32 v60, 1.0, v60
	v_add_f32_e32 v61, 1.0, v61
	v_rcp_f32_e32 v60, v60
	v_rcp_f32_e32 v61, v61
	v_add_f32_e32 v62, 1.0, v62
	v_add_f32_e32 v63, 1.0, v63
	v_rcp_f32_e32 v62, v62
	v_rcp_f32_e32 v63, v63
	v_pk_mul_f32 v[52:53], v[52:53], v[60:61]
	v_cvt_pk_bf16_f32 v56, v56, v57
	v_pk_mul_f32 v[48:49], v[48:49], v[52:53]
	v_pk_mul_f32 v[52:53], v[54:55], v[62:63]
	v_cvt_pk_bf16_f32 v48, v48, v49
	v_pk_mul_f32 v[50:51], v[50:51], v[52:53]
	v_cvt_pk_bf16_f32 v57, v58, v59
	v_cvt_pk_bf16_f32 v49, v50, v51
	v_mul_f32_e32 v50, 0xbfb8aa3b, v44
	v_mul_f32_e32 v51, 0xbfb8aa3b, v45
	v_mad_i64_i32 v[58:59], s[48:49], v68, s66, v[120:121]
	v_exp_f32_e32 v50, v50
	v_exp_f32_e32 v51, v51
	v_lshl_add_u64 v[58:59], v[58:59], 0, s[56:57]
	v_lshl_add_u64 v[58:59], v[58:59], 0, s[10:11]
	v_lshl_add_u64 v[58:59], v[58:59], 0, v[138:139]
	global_store_dwordx2 v[58:59], v[48:49], off offset:128
	v_add_f32_e32 v48, 1.0, v50
	v_add_f32_e32 v49, 1.0, v51
	v_mul_f32_e32 v50, 0xbfb8aa3b, v46
	v_mul_f32_e32 v51, 0xbfb8aa3b, v47
	v_exp_f32_e32 v50, v50
	v_exp_f32_e32 v51, v51
	v_rcp_f32_e32 v48, v48
	v_rcp_f32_e32 v49, v49
	v_add_f32_e32 v50, 1.0, v50
	v_add_f32_e32 v51, 1.0, v51
	v_rcp_f32_e32 v50, v50
	v_rcp_f32_e32 v51, v51
	v_pk_mul_f32 v[44:45], v[44:45], v[48:49]
	v_add_u32_e32 v52, 0x90, v152
	v_pk_mul_f32 v[40:41], v[40:41], v[44:45]
	v_pk_mul_f32 v[44:45], v[46:47], v[50:51]
	v_mul_f32_e32 v46, 0xbfb8aa3b, v38
	v_pk_mul_f32 v[42:43], v[42:43], v[44:45]
	v_mul_f32_e32 v44, 0xbfb8aa3b, v36
	v_mul_f32_e32 v45, 0xbfb8aa3b, v37
	v_exp_f32_e32 v44, v44
	v_exp_f32_e32 v45, v45
	v_mul_f32_e32 v47, 0xbfb8aa3b, v39
	v_exp_f32_e32 v46, v46
	v_exp_f32_e32 v47, v47
	v_add_f32_e32 v44, 1.0, v44
	v_add_f32_e32 v45, 1.0, v45
	v_rcp_f32_e32 v44, v44
	v_rcp_f32_e32 v45, v45
	v_add_f32_e32 v46, 1.0, v46
	v_add_f32_e32 v47, 1.0, v47
	v_rcp_f32_e32 v46, v46
	v_rcp_f32_e32 v47, v47
	v_pk_mul_f32 v[36:37], v[36:37], v[44:45]
	v_cvt_pk_bf16_f32 v40, v40, v41
	v_pk_mul_f32 v[32:33], v[32:33], v[36:37]
	v_pk_mul_f32 v[36:37], v[38:39], v[46:47]
	v_cvt_pk_bf16_f32 v32, v32, v33
	v_pk_mul_f32 v[34:35], v[34:35], v[36:37]
	v_cvt_pk_bf16_f32 v41, v42, v43
	v_cvt_pk_bf16_f32 v33, v34, v35
	v_mul_f32_e32 v34, 0xbfb8aa3b, v28
	v_mul_f32_e32 v35, 0xbfb8aa3b, v29
	v_mad_i64_i32 v[42:43], s[48:49], v52, s66, v[120:121]
	v_exp_f32_e32 v34, v34
	v_exp_f32_e32 v35, v35
	v_lshl_add_u64 v[42:43], v[42:43], 0, s[56:57]
	v_lshl_add_u64 v[42:43], v[42:43], 0, s[10:11]
	v_lshl_add_u64 v[42:43], v[42:43], 0, v[138:139]
	global_store_dwordx2 v[42:43], v[32:33], off offset:128
	v_add_f32_e32 v32, 1.0, v34
	v_add_f32_e32 v33, 1.0, v35
	v_mul_f32_e32 v34, 0xbfb8aa3b, v30
	v_mul_f32_e32 v35, 0xbfb8aa3b, v31
	v_exp_f32_e32 v34, v34
	v_exp_f32_e32 v35, v35
	v_rcp_f32_e32 v32, v32
	v_rcp_f32_e32 v33, v33
	v_add_f32_e32 v34, 1.0, v34
	v_add_f32_e32 v35, 1.0, v35
	v_rcp_f32_e32 v34, v34
	v_rcp_f32_e32 v35, v35
	v_pk_mul_f32 v[28:29], v[28:29], v[32:33]
	v_add_u32_e32 v36, 0xa0, v152
	v_pk_mul_f32 v[24:25], v[24:25], v[28:29]
	v_pk_mul_f32 v[28:29], v[30:31], v[34:35]
	v_mul_f32_e32 v30, 0xbfb8aa3b, v22
	v_pk_mul_f32 v[26:27], v[26:27], v[28:29]
	v_mul_f32_e32 v28, 0xbfb8aa3b, v20
	v_mul_f32_e32 v29, 0xbfb8aa3b, v21
	v_exp_f32_e32 v28, v28
	v_exp_f32_e32 v29, v29
	v_mul_f32_e32 v31, 0xbfb8aa3b, v23
	v_exp_f32_e32 v30, v30
	v_exp_f32_e32 v31, v31
	v_add_f32_e32 v28, 1.0, v28
	v_add_f32_e32 v29, 1.0, v29
	v_rcp_f32_e32 v28, v28
	v_rcp_f32_e32 v29, v29
	v_add_f32_e32 v30, 1.0, v30
	v_add_f32_e32 v31, 1.0, v31
	v_rcp_f32_e32 v30, v30
	v_rcp_f32_e32 v31, v31
	v_pk_mul_f32 v[20:21], v[20:21], v[28:29]
	v_cvt_pk_bf16_f32 v24, v24, v25
	v_pk_mul_f32 v[16:17], v[16:17], v[20:21]
	v_pk_mul_f32 v[20:21], v[22:23], v[30:31]
	v_cvt_pk_bf16_f32 v16, v16, v17
	v_pk_mul_f32 v[18:19], v[18:19], v[20:21]
	v_cvt_pk_bf16_f32 v25, v26, v27
	v_cvt_pk_bf16_f32 v17, v18, v19
	v_mul_f32_e32 v18, 0xbfb8aa3b, v12
	v_mul_f32_e32 v19, 0xbfb8aa3b, v13
	v_mad_i64_i32 v[26:27], s[48:49], v36, s66, v[120:121]
	v_exp_f32_e32 v18, v18
	v_exp_f32_e32 v19, v19
	v_lshl_add_u64 v[26:27], v[26:27], 0, s[56:57]
	v_lshl_add_u64 v[26:27], v[26:27], 0, s[10:11]
	v_lshl_add_u64 v[26:27], v[26:27], 0, v[138:139]
	global_store_dwordx2 v[26:27], v[16:17], off offset:128
	v_add_f32_e32 v16, 1.0, v18
	v_add_f32_e32 v17, 1.0, v19
	v_mul_f32_e32 v18, 0xbfb8aa3b, v14
	v_mul_f32_e32 v19, 0xbfb8aa3b, v15
	v_exp_f32_e32 v18, v18
	v_exp_f32_e32 v19, v19
	v_rcp_f32_e32 v16, v16
	v_rcp_f32_e32 v17, v17
	v_add_f32_e32 v18, 1.0, v18
	v_add_f32_e32 v19, 1.0, v19
	v_rcp_f32_e32 v18, v18
	v_rcp_f32_e32 v19, v19
	v_pk_mul_f32 v[12:13], v[12:13], v[16:17]
	v_add_u32_e32 v20, 0xb0, v152
	v_pk_mul_f32 v[8:9], v[8:9], v[12:13]
	v_pk_mul_f32 v[12:13], v[14:15], v[18:19]
	v_mul_f32_e32 v14, 0xbfb8aa3b, v6
	v_pk_mul_f32 v[10:11], v[10:11], v[12:13]
	v_mul_f32_e32 v12, 0xbfb8aa3b, v4
	v_mul_f32_e32 v13, 0xbfb8aa3b, v5
	v_exp_f32_e32 v12, v12
	v_exp_f32_e32 v13, v13
	v_mul_f32_e32 v15, 0xbfb8aa3b, v7
	v_exp_f32_e32 v14, v14
	v_exp_f32_e32 v15, v15
	v_add_f32_e32 v12, 1.0, v12
	v_add_f32_e32 v13, 1.0, v13
	v_rcp_f32_e32 v12, v12
	v_rcp_f32_e32 v13, v13
	v_add_f32_e32 v14, 1.0, v14
	v_add_f32_e32 v15, 1.0, v15
	v_rcp_f32_e32 v14, v14
	v_rcp_f32_e32 v15, v15
	v_cvt_pk_bf16_f32 v8, v8, v9
	v_cvt_pk_bf16_f32 v9, v10, v11
	v_mad_i64_i32 v[10:11], s[48:49], v20, s66, v[120:121]
	v_pk_mul_f32 v[4:5], v[4:5], v[12:13]
	v_lshl_add_u64 v[10:11], v[10:11], 0, s[56:57]
	v_pk_mul_f32 v[0:1], v[0:1], v[4:5]
	v_pk_mul_f32 v[4:5], v[6:7], v[14:15]
	v_lshl_add_u64 v[10:11], v[10:11], 0, s[10:11]
	v_pk_mul_f32 v[2:3], v[2:3], v[4:5]
	v_lshl_add_u64 v[10:11], v[10:11], 0, v[138:139]
	v_cvt_pk_bf16_f32 v0, v0, v1
	v_cvt_pk_bf16_f32 v1, v2, v3
	s_waitcnt vmcnt(5)
	buffer_store_dwordx4 v[166:169], v246, s[76:79], s5 offen nt
	buffer_store_dwordx4 v[170:173], v246, s[76:79], s5 offen offset:1024 nt
	buffer_store_dwordx4 v[174:177], v246, s[76:79], s5 offen offset:2048 nt
	buffer_store_dwordx4 v[178:181], v246, s[76:79], s5 offen offset:3072 nt
	buffer_store_dwordx4 v[182:185], v238, s[76:79], s5 offen nt
	buffer_store_dwordx4 v[186:189], v238, s[76:79], s5 offen offset:1024 nt
	buffer_store_dwordx4 v[190:193], v238, s[76:79], s5 offen offset:2048 nt
	buffer_store_dwordx4 v[194:197], v238, s[76:79], s5 offen offset:3072 nt
	buffer_store_dwordx4 v[198:201], v239, s[76:79], s5 offen nt
	buffer_store_dwordx4 v[202:205], v239, s[76:79], s5 offen offset:1024 nt
	buffer_store_dwordx4 v[206:209], v239, s[76:79], s5 offen offset:2048 nt
	buffer_store_dwordx4 v[210:213], v239, s[76:79], s5 offen offset:3072 nt
	buffer_store_dwordx4 v[158:161], v246, s[76:79], vcc_lo offen nt
	buffer_store_dwordx4 v[214:217], v246, s[76:79], vcc_lo offen offset:1024 nt
	buffer_store_dwordx4 v[218:221], v246, s[76:79], vcc_lo offen offset:2048 nt
	buffer_store_dwordx4 v[222:225], v246, s[76:79], vcc_lo offen offset:3072 nt
	buffer_store_dwordx4 v[226:229], v238, s[76:79], vcc_lo offen nt
	buffer_store_dwordx4 v[230:233], v238, s[76:79], vcc_lo offen offset:1024 nt
	buffer_store_dwordx4 v[234:237], v238, s[76:79], vcc_lo offen offset:2048 nt
	buffer_store_dwordx4 v[242:245], v238, s[76:79], vcc_lo offen offset:3072 nt
	buffer_store_dwordx4 v[112:115], v239, s[76:79], vcc_lo offen nt
	buffer_store_dwordx4 v[108:111], v239, s[76:79], vcc_lo offen offset:1024 nt
	buffer_store_dwordx4 v[116:119], v239, s[76:79], vcc_lo offen offset:2048 nt
	buffer_store_dwordx4 v[96:99], v239, s[76:79], vcc_lo offen offset:3072 nt
	s_add_u32 s5, s5, 0x30000
	s_cmp_ge_u32 s5, 0xf0000
	s_cselect_b32 s5, 0x70000000, s5
	s_andn2_b64 vcc, exec, s[6:7]
	s_mov_b64 s[6:7], -1
	global_store_dwordx2 v[122:123], v[124:125], off
	global_store_dwordx2 v[106:107], v[104:105], off
	global_store_dwordx2 v[90:91], v[88:89], off
	global_store_dwordx2 v[74:75], v[72:73], off
	global_store_dwordx2 v[58:59], v[56:57], off
	global_store_dwordx2 v[42:43], v[40:41], off
	global_store_dwordx2 v[26:27], v[24:25], off
	global_store_dwordx2 v[10:11], v[8:9], off
	global_store_dwordx2 v[10:11], v[0:1], off offset:128
	s_cbranch_vccnz .LBB0_1654
	s_andn2_b64 vcc, exec, s[22:23]
	s_cbranch_vccnz .LBB0_1653
	s_barrier
	s_branch .LBB0_1653
